# GDN scan: first fragment reads of a chunk issued right after the image barrier, ahead of prefetch issue and state conversion
# speedup vs baseline: 1.0024x; 1.0024x over previous
.LBB0_709:
	ds_read_b128 v[128:131], v161 offset:18432
	ds_read_b128 v[174:177], v161 offset:18496
	ds_read_b128 v[178:181], v161 offset:23040
	ds_read_b128 v[182:185], v161 offset:23104
	ds_read_b128 v[186:189], v161 offset:27648
	ds_read_b128 v[190:193], v161 offset:27712
	ds_read_b128 v[194:197], v161 offset:32256
	ds_read_b128 v[202:205], v161 offset:32320
	ds_read_b128 v[206:209], v161 offset:18560
	ds_read_b128 v[210:213], v161 offset:18624
	ds_read_b128 v[214:217], v161 offset:23168
	ds_read_b128 v[218:221], v161 offset:23232
	ds_read_b128 v[222:225], v161 offset:27776
	ds_read_b128 v[226:229], v161 offset:27840
	ds_read_b128 v[230:233], v161 offset:32384
	ds_read_b128 v[234:237], v161 offset:32448
	ds_read_u16 v104, v170 offset:36864
	ds_read_u16 v105, v170 offset:37152
	ds_read_u16 v106, v170 offset:37440
	ds_read_u16 v107, v170 offset:37728
	ds_read_u16 v173, v170 offset:41472
	ds_read_u16 v243, v170 offset:41760
	ds_read_u16 v244, v170 offset:42048
	ds_read_u16 v245, v170 offset:42336
	s_cmp_lg_u32 s0, 1
	s_cselect_b64 s[8:9], -1, 0
	s_cmp_eq_u32 s0, 1
	v_lshl_add_u64 v[72:73], s[92:93], 0, v[122:123]
	s_cbranch_scc1 .LBB0_711
	v_lshl_add_u64 v[16:17], s[92:93], 0, v[124:125]
	v_add_co_u32_e32 v4, vcc, 0x1a004000, v16
	v_lshl_add_u64 v[24:25], s[92:93], 0, v[126:127]
	s_nop 0
	v_addc_co_u32_e32 v5, vcc, 0, v17, vcc
	v_add_co_u32_e32 v12, vcc, 0x1c004000, v16
	s_add_u32 s10, s92, s17
	s_nop 0
	v_addc_co_u32_e32 v13, vcc, 0, v17, vcc
	v_add_co_u32_e32 v20, vcc, 0x1e004000, v16
	s_addc_u32 s11, s93, s18
	s_nop 0
	v_addc_co_u32_e32 v21, vcc, 0, v17, vcc
	v_add_co_u32_e32 v28, vcc, 0x2058000, v24
	global_load_dwordx4 v[0:3], v[4:5], off
	s_nop 0
	global_load_dwordx4 v[4:7], v[4:5], off offset:16
	v_addc_co_u32_e32 v29, vcc, 0, v25, vcc
	v_add_co_u32_e32 v36, vcc, 0x2058000, v72
	global_load_dwordx4 v[8:11], v[12:13], off
	s_nop 0
	global_load_dwordx4 v[12:15], v[12:13], off offset:16
	v_addc_co_u32_e32 v37, vcc, 0, v73, vcc
	global_load_dwordx4 v[16:19], v[20:21], off
	s_nop 0
	global_load_dwordx4 v[20:23], v[20:21], off offset:16
	s_nop 0
	global_load_dwordx4 v[24:27], v[28:29], off offset:1152
	s_nop 0
	global_load_dwordx4 v[28:31], v[28:29], off offset:1280
	s_nop 0
	global_load_dwordx4 v[32:35], v[36:37], off offset:2176
	s_nop 0
	global_load_dwordx4 v[36:39], v[36:37], off offset:2192
	s_nop 0
	global_load_dword v172, v103, s[10:11]
.LBB0_711:
	v_add_co_u32_e32 v72, vcc, 0x2001000, v72
	v_cvt_pk_bf16_f32 v92, v52, v53
	s_nop 0
	v_addc_co_u32_e32 v73, vcc, 0, v73, vcc
	global_load_dwordx4 v[76:79], v[72:73], off offset:128
	s_nop 0
	global_load_dwordx4 v[72:75], v[72:73], off offset:144
	v_cvt_pk_bf16_f32 v93, v54, v55
	v_cvt_pk_bf16_f32 v94, v48, v49
	v_cvt_pk_bf16_f32 v95, v50, v51
	v_cvt_pk_bf16_f32 v88, v44, v45
	v_cvt_pk_bf16_f32 v89, v46, v47
	v_cvt_pk_bf16_f32 v90, v40, v41
	v_cvt_pk_bf16_f32 v91, v42, v43
	v_cvt_pk_bf16_f32 v84, v60, v61
	v_cvt_pk_bf16_f32 v85, v62, v63
	v_cvt_pk_bf16_f32 v86, v56, v57
	v_cvt_pk_bf16_f32 v87, v58, v59
	v_cvt_pk_bf16_f32 v80, v64, v65
	v_cvt_pk_bf16_f32 v81, v66, v67
	v_cvt_pk_bf16_f32 v82, v68, v69
	v_cvt_pk_bf16_f32 v83, v70, v71
	s_waitcnt lgkmcnt(7)
	v_lshlrev_b32_e32 v238, 16, v104
	s_waitcnt lgkmcnt(6)
	v_lshlrev_b32_e32 v239, 16, v105
	s_waitcnt lgkmcnt(5)
	v_lshlrev_b32_e32 v240, 16, v106
	s_waitcnt lgkmcnt(4)
	v_lshlrev_b32_e32 v241, 16, v107
	s_waitcnt lgkmcnt(3)
	v_lshlrev_b32_e32 v242, 16, v173
	ds_read_u16 v104, v170 offset:46080
	ds_read_u16 v105, v170 offset:46368
	ds_read_u16 v106, v170 offset:46656
	ds_read_u16 v107, v170 offset:46944
	ds_read_u16 v173, v170 offset:50688
	ds_read_u16 v251, v170 offset:50976
	ds_read_u16 v252, v170 offset:51264
	ds_read_u16 v253, v170 offset:51552
	s_waitcnt lgkmcnt(10)
	v_lshlrev_b32_e32 v243, 16, v243
	s_waitcnt lgkmcnt(9)
	v_lshlrev_b32_e32 v244, 16, v244
	s_waitcnt lgkmcnt(8)
	v_lshlrev_b32_e32 v245, 16, v245
	s_waitcnt lgkmcnt(7)
	v_lshlrev_b32_e32 v246, 16, v104
	s_waitcnt lgkmcnt(6)
	v_lshlrev_b32_e32 v247, 16, v105
	s_waitcnt lgkmcnt(5)
	v_lshlrev_b32_e32 v248, 16, v106
	s_waitcnt lgkmcnt(4)
	v_lshlrev_b32_e32 v249, 16, v107
	s_waitcnt lgkmcnt(3)
	v_lshlrev_b32_e32 v250, 16, v173
	s_waitcnt lgkmcnt(2)
	v_lshlrev_b32_e32 v251, 16, v251
	s_waitcnt lgkmcnt(1)
	v_lshlrev_b32_e32 v252, 16, v252
	s_waitcnt lgkmcnt(0)
	v_lshlrev_b32_e32 v253, 16, v253
	v_mfma_f32_16x16x32_bf16 v[128:131], v[128:131], v[92:95], v[238:241]
	v_mfma_f32_16x16x32_bf16 v[178:181], v[178:181], v[92:95], v[242:245]
	v_mfma_f32_16x16x32_bf16 v[186:189], v[186:189], v[92:95], v[246:249]
	v_mfma_f32_16x16x32_bf16 v[194:197], v[194:197], v[92:95], v[250:253]
	v_mfma_f32_16x16x32_bf16 v[128:131], v[174:177], v[88:91], v[128:131]
	v_mfma_f32_16x16x32_bf16 v[174:177], v[182:185], v[88:91], v[178:181]
	v_mfma_f32_16x16x32_bf16 v[178:181], v[190:193], v[88:91], v[186:189]
	v_mfma_f32_16x16x32_bf16 v[182:185], v[202:205], v[88:91], v[194:197]
	s_nop 2
	ds_read_b128 v[186:189], v161
	ds_read_b128 v[190:193], v161 offset:64
	ds_read_b128 v[194:197], v161 offset:4608
	ds_read_b128 v[202:205], v161 offset:4672
	ds_read_b128 v[238:241], v161 offset:9216
	ds_read_b128 v[242:245], v161 offset:9280
	ds_read_b128 v[246:249], v161 offset:13824
	ds_read_b128 v[250:253], v161 offset:13888
	v_mfma_f32_16x16x32_bf16 v[128:131], v[206:209], v[84:87], v[128:131]
	v_mfma_f32_16x16x32_bf16 v[174:177], v[214:217], v[84:87], v[174:177]
	v_mfma_f32_16x16x32_bf16 v[178:181], v[222:225], v[84:87], v[178:181]
	v_mfma_f32_16x16x32_bf16 v[182:185], v[230:233], v[84:87], v[182:185]
	v_mfma_f32_16x16x32_bf16 v[128:131], v[210:213], v[80:83], v[128:131]
	v_mfma_f32_16x16x32_bf16 v[174:177], v[218:221], v[80:83], v[174:177]
	v_mfma_f32_16x16x32_bf16 v[178:181], v[226:229], v[80:83], v[178:181]
	v_mfma_f32_16x16x32_bf16 v[182:185], v[234:237], v[80:83], v[182:185]
	ds_read_b128 v[206:209], v161 offset:128
	ds_read_b128 v[210:213], v161 offset:192
	ds_read_b128 v[214:217], v161 offset:4736
	ds_read_b128 v[218:221], v161 offset:4800
	ds_read_b128 v[222:225], v161 offset:9344
	ds_read_b128 v[226:229], v161 offset:9408
	ds_read_b128 v[230:233], v161 offset:13952
	ds_read_b128 v[234:237], v161 offset:14016
	v_cvt_pk_bf16_f32 v128, v128, v129
	v_cvt_pk_bf16_f32 v129, v130, v131
	v_cvt_pk_bf16_f32 v130, v174, v175
	v_cvt_pk_bf16_f32 v131, v176, v177
	v_cvt_pk_bf16_f32 v174, v178, v179
	v_cvt_pk_bf16_f32 v175, v180, v181
	v_cvt_pk_bf16_f32 v176, v182, v183
	v_cvt_pk_bf16_f32 v177, v184, v185
	s_waitcnt lgkmcnt(14)
	v_mfma_f32_16x16x32_bf16 v[178:181], v[186:189], v[92:95], 0
	s_waitcnt lgkmcnt(13)
	v_mfma_f32_16x16x32_bf16 v[182:185], v[194:197], v[92:95], 0
	s_waitcnt lgkmcnt(11)
	v_mfma_f32_16x16x32_bf16 v[186:189], v[238:241], v[92:95], 0
	s_waitcnt lgkmcnt(9)
	v_mfma_f32_16x16x32_bf16 v[92:95], v[246:249], v[92:95], 0
	v_mfma_f32_16x16x32_bf16 v[178:181], v[190:193], v[88:91], v[178:181]
	v_mfma_f32_16x16x32_bf16 v[182:185], v[202:205], v[88:91], v[182:185]
	v_mfma_f32_16x16x32_bf16 v[186:189], v[242:245], v[88:91], v[186:189]
	s_waitcnt lgkmcnt(8)
	v_mfma_f32_16x16x32_bf16 v[88:91], v[250:253], v[88:91], v[92:95]
	s_nop 2
	ds_read_b128 v[92:95], v132
	ds_read_b128 v[190:193], v138
	ds_read_b128 v[194:197], v139
	ds_read_b128 v[202:205], v140
	ds_read_b128 v[238:241], v141
	ds_read_b128 v[242:245], v142
	ds_read_b128 v[246:249], v143
	ds_read_b128 v[250:253], v144
	s_waitcnt lgkmcnt(14)
	v_mfma_f32_16x16x32_bf16 v[178:181], v[206:209], v[84:87], v[178:181]
	s_waitcnt lgkmcnt(13)
	v_mfma_f32_16x16x32_bf16 v[182:185], v[214:217], v[84:87], v[182:185]
	s_waitcnt lgkmcnt(11)
	v_mfma_f32_16x16x32_bf16 v[186:189], v[222:225], v[84:87], v[186:189]
	s_waitcnt lgkmcnt(9)
	v_mfma_f32_16x16x32_bf16 v[84:87], v[230:233], v[84:87], v[88:91]
	v_mfma_f32_16x16x32_bf16 v[88:91], v[210:213], v[80:83], v[178:181]
	v_mfma_f32_16x16x32_bf16 v[178:181], v[218:221], v[80:83], v[182:185]
	s_nop 2
	ds_read_b128 v[182:185], v133
	ds_read_b128 v[206:209], v145
	ds_read_b128 v[210:213], v146
	ds_read_b128 v[214:217], v147
	v_mfma_f32_16x16x32_bf16 v[186:189], v[226:229], v[80:83], v[186:189]
	ds_read_b128 v[218:221], v148
	ds_read_b128 v[222:225], v149
	ds_read_b128 v[226:229], v150
	ds_read_b128 v[230:233], v151
	s_waitcnt lgkmcnt(14)
	v_mfma_f32_16x16x32_bf16 v[80:83], v[234:237], v[80:83], v[84:87]
	v_mfma_f32_16x16x32_bf16 v[84:87], v[92:95], v[128:131], 0
	s_waitcnt lgkmcnt(13)
	v_mfma_f32_16x16x32_bf16 v[92:95], v[194:197], v[128:131], 0
	s_waitcnt lgkmcnt(11)
	v_mfma_f32_16x16x32_bf16 v[194:197], v[238:241], v[128:131], 0
	s_waitcnt lgkmcnt(9)
	v_mfma_f32_16x16x32_bf16 v[128:131], v[246:249], v[128:131], 0
	v_mfma_f32_16x16x32_bf16 v[84:87], v[190:193], v[174:177], v[84:87]
	v_mfma_f32_16x16x32_bf16 v[92:95], v[202:205], v[174:177], v[92:95]
	v_mfma_f32_16x16x32_bf16 v[190:193], v[242:245], v[174:177], v[194:197]
	s_waitcnt lgkmcnt(8)
	v_mfma_f32_16x16x32_bf16 v[128:131], v[250:253], v[174:177], v[128:131]
	ds_read_b128 v[174:177], v119 offset:55296
	ds_read_b128 v[194:197], v119 offset:55360
	ds_read_b128 v[202:205], v119 offset:57856
	ds_read_b128 v[234:237], v119 offset:57920
	ds_read_b128 v[238:241], v119 offset:60416
	ds_read_b128 v[242:245], v119 offset:60480
	ds_read_b128 v[246:249], v119 offset:62976
	ds_read_b128 v[250:253], v119 offset:63040
	v_cvt_pk_bf16_f32 v104, v84, v85
	v_cvt_pk_bf16_f32 v105, v86, v87
	v_cvt_pk_bf16_f32 v106, v92, v93
	v_cvt_pk_bf16_f32 v107, v94, v95
	v_cvt_pk_bf16_f32 v94, v128, v129
	v_cvt_pk_bf16_f32 v95, v130, v131
	s_waitcnt lgkmcnt(14)
	v_mfma_f32_16x16x32_bf16 v[84:87], v[182:185], v[104:107], v[88:91]
	v_cvt_pk_bf16_f32 v92, v190, v191
	v_cvt_pk_bf16_f32 v93, v192, v193
	v_pk_mul_f32 v[54:55], v[54:55], v[118:119] op_sel_hi:[1,0]
	s_waitcnt lgkmcnt(13)
	v_mfma_f32_16x16x32_bf16 v[88:91], v[210:213], v[104:107], v[178:181]
	v_mul_f32_e64 v52, v52, v118
	v_mul_f32_e64 v53, v53, v118
	v_pk_mul_f32 v[50:51], v[50:51], v[118:119] op_sel_hi:[1,0]
	v_pk_mul_f32 v[48:49], v[48:49], v[118:119] op_sel_hi:[1,0]
	s_waitcnt lgkmcnt(11)
	v_mfma_f32_16x16x32_bf16 v[128:131], v[218:221], v[104:107], v[186:189]
	v_mul_f32_e64 v46, v46, v118
	v_mul_f32_e64 v47, v47, v118
	v_pk_mul_f32 v[44:45], v[44:45], v[118:119] op_sel_hi:[1,0]
	v_pk_mul_f32 v[42:43], v[42:43], v[118:119] op_sel_hi:[1,0]
	v_mfma_f32_16x16x32_bf16 v[178:181], v[206:209], v[92:95], v[84:87]
	v_mul_f32_e64 v40, v40, v118
	v_mul_f32_e64 v41, v41, v118
	v_pk_mul_f32 v[62:63], v[62:63], v[118:119] op_sel_hi:[1,0]
	v_pk_mul_f32 v[60:61], v[60:61], v[118:119] op_sel_hi:[1,0]
	v_mfma_f32_16x16x32_bf16 v[88:91], v[214:217], v[92:95], v[88:91]
	v_mul_f32_e64 v58, v58, v118
	v_mul_f32_e64 v59, v59, v118
	v_pk_mul_f32 v[56:57], v[56:57], v[118:119] op_sel_hi:[1,0]
	v_pk_mul_f32 v[66:67], v[66:67], v[118:119] op_sel_hi:[1,0]
	s_waitcnt lgkmcnt(10)
	v_mfma_f32_16x16x32_bf16 v[84:87], v[222:225], v[92:95], v[128:131]
	s_nop 2
	ds_read_b128 v[128:131], v135
	ds_read_b128 v[182:185], v152
	ds_read_b128 v[186:189], v153
	ds_read_b128 v[190:193], v154
	ds_read_b128 v[206:209], v155
	ds_read_b128 v[210:213], v156
	ds_read_b128 v[214:217], v157
	ds_read_b128 v[218:221], v158
	v_pk_mul_f32 v[64:65], v[64:65], v[118:119] op_sel_hi:[1,0]
	v_pk_mul_f32 v[70:71], v[70:71], v[118:119] op_sel_hi:[1,0]
	s_waitcnt lgkmcnt(14)
	v_mfma_f32_16x16x32_bf16 v[80:83], v[226:229], v[104:107], v[80:83]
	v_mul_f32_e64 v68, v68, v118
	v_mul_f32_e64 v69, v69, v118
	v_mfma_f32_16x16x32_bf16 v[80:83], v[230:233], v[92:95], v[80:83]
	v_mfma_f32_16x16x32_bf16 v[52:55], v[174:177], v[104:107], v[52:55]
	s_waitcnt lgkmcnt(13)
	v_mfma_f32_16x16x32_bf16 v[48:51], v[202:205], v[104:107], v[48:51]
	s_waitcnt lgkmcnt(11)
	v_mfma_f32_16x16x32_bf16 v[44:47], v[238:241], v[104:107], v[44:47]
	s_waitcnt lgkmcnt(9)
	v_mfma_f32_16x16x32_bf16 v[40:43], v[246:249], v[104:107], v[40:43]
	v_mfma_f32_16x16x32_bf16 v[52:55], v[194:197], v[92:95], v[52:55]
	v_mfma_f32_16x16x32_bf16 v[48:51], v[234:237], v[92:95], v[48:51]
	v_mfma_f32_16x16x32_bf16 v[44:47], v[242:245], v[92:95], v[44:47]
	s_waitcnt lgkmcnt(8)
	v_mfma_f32_16x16x32_bf16 v[40:43], v[250:253], v[92:95], v[40:43]
	s_waitcnt lgkmcnt(7)
	v_mfma_f32_16x16x32_bf16 v[60:63], v[128:131], v[104:107], v[60:63]
	s_waitcnt lgkmcnt(5)
	v_mfma_f32_16x16x32_bf16 v[56:59], v[186:189], v[104:107], v[56:59]
	s_waitcnt lgkmcnt(3)
	v_mfma_f32_16x16x32_bf16 v[64:67], v[206:209], v[104:107], v[64:67]
	s_waitcnt lgkmcnt(1)
	v_mfma_f32_16x16x32_bf16 v[68:71], v[214:217], v[104:107], v[68:71]
	v_mfma_f32_16x16x32_bf16 v[60:63], v[182:185], v[92:95], v[60:63]
	v_mfma_f32_16x16x32_bf16 v[56:59], v[190:193], v[92:95], v[56:59]
	v_mfma_f32_16x16x32_bf16 v[64:67], v[210:213], v[92:95], v[64:67]
	s_waitcnt lgkmcnt(0)
	v_mfma_f32_16x16x32_bf16 v[68:71], v[218:221], v[92:95], v[68:71]
	v_mul_f32_e32 v106, v168, v179
	v_pk_mul_f32 v[104:105], v[180:181], v[180:181]
	v_pk_mul_f32 v[92:93], v[178:179], v[178:179]
	v_cvt_pk_bf16_f32 v106, v106, s0
	v_mul_f32_e32 v94, v168, v178
	v_mov_b32_dpp v92, v92 quad_perm:[1,0,3,2] row_mask:0xf bank_mask:0xf bound_ctrl:1
	v_mov_b32_dpp v93, v93 quad_perm:[1,0,3,2] row_mask:0xf bank_mask:0xf bound_ctrl:1
	ds_write_b16 v171, v106 offset:288
	v_mov_b32_dpp v104, v104 quad_perm:[1,0,3,2] row_mask:0xf bank_mask:0xf bound_ctrl:1
	v_mul_f32_e32 v106, v168, v180
	v_mov_b32_dpp v105, v105 quad_perm:[1,0,3,2] row_mask:0xf bank_mask:0xf bound_ctrl:1
	v_cvt_pk_bf16_f32 v94, v94, s0
	v_pk_fma_f32 v[92:93], v[178:179], v[178:179], v[92:93]
	v_cvt_pk_bf16_f32 v106, v106, s0
	v_pk_fma_f32 v[104:105], v[180:181], v[180:181], v[104:105]
	ds_write_b16 v171, v94
	v_mov_b32_dpp v94, v92 quad_perm:[2,3,0,1] row_mask:0xf bank_mask:0xf bound_ctrl:1
	v_mov_b32_dpp v95, v93 quad_perm:[2,3,0,1] row_mask:0xf bank_mask:0xf bound_ctrl:1
	ds_write_b16 v171, v106 offset:576
	v_mov_b32_dpp v106, v104 quad_perm:[2,3,0,1] row_mask:0xf bank_mask:0xf bound_ctrl:1
	v_mov_b32_dpp v107, v105 quad_perm:[2,3,0,1] row_mask:0xf bank_mask:0xf bound_ctrl:1
	v_pk_add_f32 v[92:93], v[92:93], v[94:95]
	v_pk_add_f32 v[104:105], v[104:105], v[106:107]
	s_nop 0
	v_mov_b32_dpp v94, v92 row_half_mirror row_mask:0xf bank_mask:0xf bound_ctrl:1
	v_mov_b32_dpp v95, v93 row_half_mirror row_mask:0xf bank_mask:0xf bound_ctrl:1
	v_mov_b32_dpp v106, v104 row_half_mirror row_mask:0xf bank_mask:0xf bound_ctrl:1
	v_mov_b32_dpp v107, v105 row_half_mirror row_mask:0xf bank_mask:0xf bound_ctrl:1
	v_pk_add_f32 v[92:93], v[92:93], v[94:95]
	v_pk_add_f32 v[128:129], v[104:105], v[106:107]
	v_mul_f32_e32 v104, v168, v181
	v_mov_b32_dpp v94, v92 row_mirror row_mask:0xf bank_mask:0xf bound_ctrl:1
	v_mov_b32_dpp v95, v93 row_mirror row_mask:0xf bank_mask:0xf bound_ctrl:1
	v_mov_b32_dpp v130, v128 row_mirror row_mask:0xf bank_mask:0xf bound_ctrl:1
	v_mov_b32_dpp v131, v129 row_mirror row_mask:0xf bank_mask:0xf bound_ctrl:1
	v_cvt_pk_bf16_f32 v104, v104, s0
	ds_write_b16 v171, v104 offset:864
	s_and_saveexec_b64 s[10:11], s[4:5]
	v_pk_add_f32 v[106:107], v[128:129], v[130:131]
	v_pk_add_f32 v[104:105], v[92:93], v[94:95]
	ds_write_b128 v169, v[104:107]
	s_or_b64 exec, exec, s[10:11]
	v_pk_mul_f32 v[92:93], v[88:89], v[88:89]
	v_mul_f32_e32 v94, v168, v88
	v_pk_mul_f32 v[104:105], v[90:91], v[90:91]
	v_mov_b32_dpp v92, v92 quad_perm:[1,0,3,2] row_mask:0xf bank_mask:0xf bound_ctrl:1
	v_mov_b32_dpp v93, v93 quad_perm:[1,0,3,2] row_mask:0xf bank_mask:0xf bound_ctrl:1
	v_pk_fma_f32 v[92:93], v[88:89], v[88:89], v[92:93]
	v_mul_f32_e32 v88, v168, v89
	v_mul_f32_e32 v89, v168, v90
	v_cvt_pk_bf16_f32 v88, v88, s0
	v_cvt_pk_bf16_f32 v89, v89, s0
	ds_write_b16 v171, v88 offset:4896
	v_mov_b32_dpp v88, v104 quad_perm:[1,0,3,2] row_mask:0xf bank_mask:0xf bound_ctrl:1
	ds_write_b16 v171, v89 offset:5184
	v_mov_b32_dpp v89, v105 quad_perm:[1,0,3,2] row_mask:0xf bank_mask:0xf bound_ctrl:1
	v_cvt_pk_bf16_f32 v94, v94, s0
	v_pk_fma_f32 v[88:89], v[90:91], v[90:91], v[88:89]
	ds_write_b16 v171, v94 offset:4608
	v_mov_b32_dpp v94, v92 quad_perm:[2,3,0,1] row_mask:0xf bank_mask:0xf bound_ctrl:1
	v_mov_b32_dpp v95, v93 quad_perm:[2,3,0,1] row_mask:0xf bank_mask:0xf bound_ctrl:1
	v_mov_b32_dpp v104, v88 quad_perm:[2,3,0,1] row_mask:0xf bank_mask:0xf bound_ctrl:1
	v_mov_b32_dpp v105, v89 quad_perm:[2,3,0,1] row_mask:0xf bank_mask:0xf bound_ctrl:1
	v_pk_add_f32 v[92:93], v[92:93], v[94:95]
	v_pk_add_f32 v[88:89], v[88:89], v[104:105]
	v_mul_f32_e32 v90, v168, v91
	v_mov_b32_dpp v94, v92 row_half_mirror row_mask:0xf bank_mask:0xf bound_ctrl:1
	v_mov_b32_dpp v95, v93 row_half_mirror row_mask:0xf bank_mask:0xf bound_ctrl:1
	v_mov_b32_dpp v104, v88 row_half_mirror row_mask:0xf bank_mask:0xf bound_ctrl:1
	v_mov_b32_dpp v105, v89 row_half_mirror row_mask:0xf bank_mask:0xf bound_ctrl:1
	v_pk_add_f32 v[92:93], v[92:93], v[94:95]
	v_pk_add_f32 v[88:89], v[88:89], v[104:105]
	v_cvt_pk_bf16_f32 v90, v90, s0
	v_mov_b32_dpp v94, v92 row_mirror row_mask:0xf bank_mask:0xf bound_ctrl:1
	v_mov_b32_dpp v95, v93 row_mirror row_mask:0xf bank_mask:0xf bound_ctrl:1
	v_mov_b32_dpp v128, v88 row_mirror row_mask:0xf bank_mask:0xf bound_ctrl:1
	v_mov_b32_dpp v129, v89 row_mirror row_mask:0xf bank_mask:0xf bound_ctrl:1
	ds_write_b16 v171, v90 offset:5472
	s_and_saveexec_b64 s[10:11], s[4:5]
	v_pk_add_f32 v[90:91], v[88:89], v[128:129]
	v_pk_add_f32 v[88:89], v[92:93], v[94:95]
	ds_write_b128 v169, v[88:91] offset:64
	s_or_b64 exec, exec, s[10:11]
	v_pk_mul_f32 v[88:89], v[84:85], v[84:85]
	v_mul_f32_e32 v90, v168, v84
	v_pk_mul_f32 v[92:93], v[86:87], v[86:87]
	v_mov_b32_dpp v88, v88 quad_perm:[1,0,3,2] row_mask:0xf bank_mask:0xf bound_ctrl:1
	v_mov_b32_dpp v89, v89 quad_perm:[1,0,3,2] row_mask:0xf bank_mask:0xf bound_ctrl:1
	v_pk_fma_f32 v[88:89], v[84:85], v[84:85], v[88:89]
	v_mul_f32_e32 v84, v168, v85
	v_mul_f32_e32 v85, v168, v86
	v_cvt_pk_bf16_f32 v84, v84, s0
	v_cvt_pk_bf16_f32 v85, v85, s0
	ds_write_b16 v171, v84 offset:9504
	v_mov_b32_dpp v84, v92 quad_perm:[1,0,3,2] row_mask:0xf bank_mask:0xf bound_ctrl:1
	ds_write_b16 v171, v85 offset:9792
	v_mov_b32_dpp v85, v93 quad_perm:[1,0,3,2] row_mask:0xf bank_mask:0xf bound_ctrl:1
	v_cvt_pk_bf16_f32 v90, v90, s0
	v_pk_fma_f32 v[84:85], v[86:87], v[86:87], v[84:85]
	ds_write_b16 v171, v90 offset:9216
	v_mov_b32_dpp v90, v88 quad_perm:[2,3,0,1] row_mask:0xf bank_mask:0xf bound_ctrl:1
	v_mov_b32_dpp v91, v89 quad_perm:[2,3,0,1] row_mask:0xf bank_mask:0xf bound_ctrl:1
	v_mov_b32_dpp v92, v84 quad_perm:[2,3,0,1] row_mask:0xf bank_mask:0xf bound_ctrl:1
	v_mov_b32_dpp v93, v85 quad_perm:[2,3,0,1] row_mask:0xf bank_mask:0xf bound_ctrl:1
	v_pk_add_f32 v[88:89], v[88:89], v[90:91]
	v_pk_add_f32 v[84:85], v[84:85], v[92:93]
	v_mul_f32_e32 v86, v168, v87
	v_mov_b32_dpp v90, v88 row_half_mirror row_mask:0xf bank_mask:0xf bound_ctrl:1
	v_mov_b32_dpp v91, v89 row_half_mirror row_mask:0xf bank_mask:0xf bound_ctrl:1
	v_mov_b32_dpp v92, v84 row_half_mirror row_mask:0xf bank_mask:0xf bound_ctrl:1
	v_mov_b32_dpp v93, v85 row_half_mirror row_mask:0xf bank_mask:0xf bound_ctrl:1
	v_pk_add_f32 v[88:89], v[88:89], v[90:91]
	v_pk_add_f32 v[84:85], v[84:85], v[92:93]
	v_cvt_pk_bf16_f32 v86, v86, s0
	v_mov_b32_dpp v90, v88 row_mirror row_mask:0xf bank_mask:0xf bound_ctrl:1
	v_mov_b32_dpp v91, v89 row_mirror row_mask:0xf bank_mask:0xf bound_ctrl:1
	v_mov_b32_dpp v92, v84 row_mirror row_mask:0xf bank_mask:0xf bound_ctrl:1
	v_mov_b32_dpp v93, v85 row_mirror row_mask:0xf bank_mask:0xf bound_ctrl:1
	ds_write_b16 v171, v86 offset:10080
	s_and_saveexec_b64 s[10:11], s[4:5]
	v_pk_add_f32 v[86:87], v[84:85], v[92:93]
	v_pk_add_f32 v[84:85], v[88:89], v[90:91]
	ds_write_b128 v169, v[84:87] offset:128
	s_or_b64 exec, exec, s[10:11]
	v_pk_mul_f32 v[84:85], v[80:81], v[80:81]
	v_mul_f32_e32 v86, v168, v80
	v_pk_mul_f32 v[88:89], v[82:83], v[82:83]
	v_mov_b32_dpp v84, v84 quad_perm:[1,0,3,2] row_mask:0xf bank_mask:0xf bound_ctrl:1
	v_mov_b32_dpp v85, v85 quad_perm:[1,0,3,2] row_mask:0xf bank_mask:0xf bound_ctrl:1
	v_pk_fma_f32 v[84:85], v[80:81], v[80:81], v[84:85]
	v_mul_f32_e32 v80, v168, v81
	v_mul_f32_e32 v81, v168, v82
	v_cvt_pk_bf16_f32 v80, v80, s0
	v_cvt_pk_bf16_f32 v81, v81, s0
	ds_write_b16 v171, v80 offset:14112
	v_mov_b32_dpp v80, v88 quad_perm:[1,0,3,2] row_mask:0xf bank_mask:0xf bound_ctrl:1
	ds_write_b16 v171, v81 offset:14400
	v_mov_b32_dpp v81, v89 quad_perm:[1,0,3,2] row_mask:0xf bank_mask:0xf bound_ctrl:1
	v_cvt_pk_bf16_f32 v86, v86, s0
	v_pk_fma_f32 v[80:81], v[82:83], v[82:83], v[80:81]
	ds_write_b16 v171, v86 offset:13824
	v_mov_b32_dpp v86, v84 quad_perm:[2,3,0,1] row_mask:0xf bank_mask:0xf bound_ctrl:1
	v_mov_b32_dpp v87, v85 quad_perm:[2,3,0,1] row_mask:0xf bank_mask:0xf bound_ctrl:1
	v_mov_b32_dpp v88, v80 quad_perm:[2,3,0,1] row_mask:0xf bank_mask:0xf bound_ctrl:1
	v_mov_b32_dpp v89, v81 quad_perm:[2,3,0,1] row_mask:0xf bank_mask:0xf bound_ctrl:1
	v_pk_add_f32 v[84:85], v[84:85], v[86:87]
	v_pk_add_f32 v[80:81], v[80:81], v[88:89]
	v_mul_f32_e32 v82, v168, v83
	v_mov_b32_dpp v86, v84 row_half_mirror row_mask:0xf bank_mask:0xf bound_ctrl:1
	v_mov_b32_dpp v87, v85 row_half_mirror row_mask:0xf bank_mask:0xf bound_ctrl:1
	v_mov_b32_dpp v88, v80 row_half_mirror row_mask:0xf bank_mask:0xf bound_ctrl:1
	v_mov_b32_dpp v89, v81 row_half_mirror row_mask:0xf bank_mask:0xf bound_ctrl:1
	v_pk_add_f32 v[84:85], v[84:85], v[86:87]
	v_pk_add_f32 v[80:81], v[80:81], v[88:89]
	v_cvt_pk_bf16_f32 v82, v82, s0
	v_mov_b32_dpp v86, v84 row_mirror row_mask:0xf bank_mask:0xf bound_ctrl:1
	v_mov_b32_dpp v87, v85 row_mirror row_mask:0xf bank_mask:0xf bound_ctrl:1
	v_mov_b32_dpp v88, v80 row_mirror row_mask:0xf bank_mask:0xf bound_ctrl:1
	v_mov_b32_dpp v89, v81 row_mirror row_mask:0xf bank_mask:0xf bound_ctrl:1
	ds_write_b16 v171, v82 offset:14688
	s_and_saveexec_b64 s[10:11], s[4:5]
	v_pk_add_f32 v[82:83], v[80:81], v[88:89]
	v_pk_add_f32 v[80:81], v[84:85], v[86:87]
	ds_write_b128 v169, v[80:83] offset:192
	s_or_b64 exec, exec, s[10:11]
	s_andn2_b64 vcc, exec, s[8:9]
	s_waitcnt lgkmcnt(0)
	s_barrier
	s_cbranch_vccnz .LBB0_708
	s_waitcnt vmcnt(2)
	v_mov_b32_e32 v118, v172
	ds_write_b128 v164, v[0:3]
	ds_write_b128 v164, v[4:7] offset:16
	ds_write_b128 v164, v[8:11] offset:18432
	ds_write_b128 v164, v[12:15] offset:18448
	ds_write_b128 v164, v[16:19] offset:36864
	ds_write_b128 v164, v[20:23] offset:36880
	ds_write_b128 v165, v[32:35] offset:55296
	ds_write_b128 v165, v[36:39] offset:55312
	ds_write_b128 v166, v[24:27]
	ds_write_b128 v167, v[28:31]
	s_branch .LBB0_708
